# GEMM-up epilogue: IEEE division sequences of silu done two at a time with packed f32 FMA steps (bit-identical)
# speedup vs baseline: 1.0239x; 1.0012x over previous
; #define UFOR(v, n) _Pragma("unroll") for (int v = 0; v < (n); ++v)
; __device__ __forceinline__ unsigned pk2(float a, float b) { return (unsigned)f2bf(a) | ((unsigned)f2bf(b) << 16); }
; __device__ __forceinline__ float siluf_(float x) { return x / (1.f + __expf(-x)); }
; template <int EPI, int K, int KL> ...
;     ...
;         const long gr = brow + lr;
;         const bool valid = (gr >= seq0) && (gr < seq1) && (lr >= 1 || gr == seq0) && (lr <= 254 || gr == seq1 - 1);
;         if (valid) {
;           const float mp = (gr - 1 >= seq0) ? 1.f : 0.f, mn = (gr + 1 < seq1) ? 1.f : 0.f;
;           float o[4];
;           UFOR(x, 4) {
;             const float g = wg[x][0] * pg[x] * mp + wg[x][1] * cgv[x] + wg[x][2] * ng[x] * mn;
;             const float v = wv[x][0] * pvv[x] * mp + wv[x][1] * cv[x] + wv[x][2] * nv[x] * mn;
;             o[x] = siluf_(g) * v;
;           }
;           uint2 pk; pk.x = pk2(o[0], o[1]); pk.y = pk2(o[2], o[3]);
;           *(uint2*)(e.h2 + (size_t)gr * DFF + gc) = pk;
;         }
.LBB0_1112:
	v_lshl_add_u64 v[52:53], v[132:133], 0, s[58:59]
	v_min_i32_e32 v36, 0xfe, v52
	v_lshl_add_u32 v36, v36, 9, v64
	v_lshl_add_u64 v[54:55], v[28:29], 0, s[58:59]
	ds_read2_b64 v[40:43], v36 offset0:64 offset1:96
	v_cmp_le_i64_e32 vcc, s[50:51], v[54:55]
	v_cmp_gt_i64_e64 s[42:43], s[52:53], v[54:55]
	s_and_b64 s[62:63], vcc, s[42:43]
	v_cmp_lt_i32_e32 vcc, 0, v52
	v_cmp_eq_u64_e64 s[42:43], s[58:59], v[10:11]
	s_or_b64 s[42:43], vcc, s[42:43]
	s_and_b64 s[62:63], s[62:63], s[42:43]
	v_cmp_gt_i32_e32 vcc, s27, v52
	v_cmp_eq_u64_e64 s[42:43], s[58:59], v[32:33]
	s_or_b64 s[42:43], vcc, s[42:43]
	s_waitcnt lgkmcnt(0)
	v_lshlrev_b32_e32 v36, 16, v40
	v_lshlrev_b32_e32 v37, 16, v41
	v_and_b32_e32 v39, 0xffff0000, v41
	v_and_b32_e32 v38, 0xffff0000, v40
	v_lshlrev_b32_e32 v40, 16, v42
	v_lshlrev_b32_e32 v41, 16, v43
	v_and_b32_e32 v43, 0xffff0000, v43
	v_and_b32_e32 v42, 0xffff0000, v42
	s_and_b64 s[62:63], s[62:63], s[42:43]
	s_and_saveexec_b64 s[42:43], s[62:63]
	s_cbranch_execz .LBB0_1114
	v_cmp_lt_i64_e32 vcc, s[50:51], v[54:55]
	v_pk_mul_f32 v[58:59], v[12:13], v[58:59]
	v_pk_mul_f32 v[56:57], v[22:23], v[56:57]
	v_cndmask_b32_e64 v66, 0, 1.0, vcc
	v_cmp_gt_i64_e32 vcc, s[56:57], v[54:55]
	v_pk_mul_f32 v[58:59], v[58:59], v[66:67] op_sel_hi:[1,0]
	v_pk_mul_f32 v[70:71], v[14:15], v[36:37]
	v_cndmask_b32_e64 v68, 0, 1.0, vcc
	v_pk_fma_f32 v[58:59], v[0:1], v[46:47], v[58:59]
	v_pk_mul_f32 v[56:57], v[56:57], v[66:67] op_sel_hi:[1,0]
	v_pk_mul_f32 v[74:75], v[20:21], v[38:39]
	v_pk_fma_f32 v[58:59], v[70:71], v[68:69], v[58:59] op_sel_hi:[1,0,1]
	v_pk_fma_f32 v[56:57], v[8:9], v[44:45], v[56:57]
	v_mul_f32_e32 v53, 0xbfb8aa3b, v58
	v_pk_fma_f32 v[56:57], v[74:75], v[68:69], v[56:57] op_sel_hi:[1,0,1]
	v_exp_f32_e32 v70, v53
	v_mul_f32_e32 v53, 0xbfb8aa3b, v56
	v_exp_f32_e32 v74, v53
	v_mul_f32_e32 v53, 0xbfb8aa3b, v59
	v_exp_f32_e32 v71, v53
	v_pk_mul_f32 v[62:63], v[4:5], v[62:63]
	v_pk_mul_f32 v[72:73], v[6:7], v[40:41]
	v_pk_mul_f32 v[62:63], v[62:63], v[66:67] op_sel_hi:[1,0]
	v_pk_add_f32 v[70:71], v[70:71], 1.0 op_sel_hi:[1,0]
	v_pk_fma_f32 v[62:63], v[24:25], v[50:51], v[62:63]
	v_pk_fma_f32 v[62:63], v[68:69], v[72:73], v[62:63] op_sel_hi:[0,1,1]
	v_pk_mul_f32 v[60:61], v[18:19], v[60:61]
	v_pk_mul_f32 v[76:77], v[2:3], v[42:43]
	s_nop 0
	v_div_scale_f32 v80, vcc, v70, v70, v58
	v_div_scale_f32 v81, vcc, v71, v71, v59
	v_rcp_f32_e32 v82, v80
	v_rcp_f32_e32 v83, v81
	v_div_scale_f32 v86, s[62:63], v58, v70, v58
	v_div_scale_f32 v87, vcc, v59, v71, v59
	v_pk_fma_f32 v[84:85], v[80:81], v[82:83], 1.0 op_sel_hi:[1,1,0] neg_lo:[1,0,0] neg_hi:[1,0,0]
	v_pk_fma_f32 v[82:83], v[84:85], v[82:83], v[82:83]
	v_pk_mul_f32 v[88:89], v[86:87], v[82:83]
	v_pk_fma_f32 v[84:85], v[80:81], v[88:89], v[86:87] neg_lo:[1,0,0] neg_hi:[1,0,0]
	v_pk_fma_f32 v[88:89], v[84:85], v[82:83], v[88:89]
	v_pk_fma_f32 v[84:85], v[80:81], v[88:89], v[86:87] neg_lo:[1,0,0] neg_hi:[1,0,0]
	v_div_fmas_f32 v85, v85, v83, v89
	s_mov_b64 vcc, s[62:63]
	s_nop 0
	v_div_fmas_f32 v84, v84, v82, v88
	v_div_fixup_f32 v59, v85, v71, v59
	v_div_fixup_f32 v58, v84, v70, v58
	v_mul_f32_e32 v53, 0xbfb8aa3b, v57
	v_exp_f32_e32 v75, v53
	v_pk_mul_f32 v[58:59], v[62:63], v[58:59]
	v_pk_mul_f32 v[60:61], v[60:61], v[66:67] op_sel_hi:[1,0]
	v_pk_add_f32 v[62:63], v[74:75], 1.0 op_sel_hi:[1,0]
	s_nop 0
	v_pk_fma_f32 v[60:61], v[16:17], v[48:49], v[60:61]
	v_pk_fma_f32 v[60:61], v[68:69], v[76:77], v[60:61] op_sel_hi:[0,1,1]
	s_nop 0
	v_div_scale_f32 v80, vcc, v62, v62, v56
	v_div_scale_f32 v81, vcc, v63, v63, v57
	v_rcp_f32_e32 v82, v80
	v_rcp_f32_e32 v83, v81
	v_div_scale_f32 v86, s[62:63], v56, v62, v56
	v_div_scale_f32 v87, vcc, v57, v63, v57
	v_pk_fma_f32 v[84:85], v[80:81], v[82:83], 1.0 op_sel_hi:[1,1,0] neg_lo:[1,0,0] neg_hi:[1,0,0]
	v_pk_fma_f32 v[82:83], v[84:85], v[82:83], v[82:83]
	v_pk_mul_f32 v[88:89], v[86:87], v[82:83]
	v_pk_fma_f32 v[84:85], v[80:81], v[88:89], v[86:87] neg_lo:[1,0,0] neg_hi:[1,0,0]
	v_pk_fma_f32 v[88:89], v[84:85], v[82:83], v[88:89]
	v_pk_fma_f32 v[84:85], v[80:81], v[88:89], v[86:87] neg_lo:[1,0,0] neg_hi:[1,0,0]
	v_div_fmas_f32 v85, v85, v83, v89
	s_mov_b64 vcc, s[62:63]
	s_nop 0
	v_div_fmas_f32 v84, v84, v82, v88
	v_div_fixup_f32 v57, v85, v63, v57
	v_div_fixup_f32 v56, v84, v62, v56
	v_pk_mul_f32 v[56:57], v[60:61], v[56:57]
	v_cvt_pk_bf16_f32 v56, v58, v56
	v_cvt_pk_bf16_f32 v57, v59, v57
	v_add_co_u32_e32 v58, vcc, 0xffffe000, v30
	s_nop 0
	v_addc_co_u32_e32 v59, vcc, -1, v31, vcc
	global_store_dwordx2 v[58:59], v[56:57], off offset:-3072
; #define UFOR(v, n) _Pragma("unroll") for (int v = 0; v < (n); ++v)
; __device__ __forceinline__ unsigned pk2(float a, float b) { return (unsigned)f2bf(a) | ((unsigned)f2bf(b) << 16); }
; __device__ __forceinline__ float siluf_(float x) { return x / (1.f + __expf(-x)); }
; template <int EPI, int K, int KL> ...
;     ...
;         const long gr = brow + lr;
;         const bool valid = (gr >= seq0) && (gr < seq1) && (lr >= 1 || gr == seq0) && (lr <= 254 || gr == seq1 - 1);
;         if (valid) {
;           const float mp = (gr - 1 >= seq0) ? 1.f : 0.f, mn = (gr + 1 < seq1) ? 1.f : 0.f;
;           float o[4];
;           UFOR(x, 4) {
;             const float g = wg[x][0] * pg[x] * mp + wg[x][1] * cgv[x] + wg[x][2] * ng[x] * mn;
;             const float v = wv[x][0] * pvv[x] * mp + wv[x][1] * cv[x] + wv[x][2] * nv[x] * mn;
;             o[x] = siluf_(g) * v;
;           }
;           uint2 pk; pk.x = pk2(o[0], o[1]); pk.y = pk2(o[2], o[3]);
;           *(uint2*)(e.h2 + (size_t)gr * DFF + gc) = pk;
;         }
.LBB0_1114:
	s_or_b64 exec, exec, s[42:43]
	v_add_u32_e32 v62, 1, v52
	v_min_i32_e32 v52, 0xfe, v62
	v_lshl_add_u32 v52, v52, 9, v64
	v_lshl_add_u64 v[54:55], v[54:55], 0, 1
	ds_read2_b64 v[58:61], v52 offset0:64 offset1:96
	v_cmp_le_i64_e32 vcc, s[50:51], v[54:55]
	v_cmp_gt_i64_e64 s[42:43], s[52:53], v[54:55]
	s_and_b64 s[42:43], vcc, s[42:43]
	v_cmp_eq_u64_e32 vcc, s[58:59], v[26:27]
	s_or_b64 s[62:63], s[40:41], vcc
	s_and_b64 s[62:63], s[42:43], s[62:63]
	v_cmp_gt_i32_e32 vcc, s27, v62
	v_cmp_eq_u64_e64 s[42:43], s[58:59], v[34:35]
	s_or_b64 s[42:43], vcc, s[42:43]
	s_waitcnt lgkmcnt(0)
	v_lshlrev_b32_e32 v52, 16, v58
	v_lshlrev_b32_e32 v53, 16, v59
	v_and_b32_e32 v57, 0xffff0000, v59
	v_and_b32_e32 v56, 0xffff0000, v58
	v_lshlrev_b32_e32 v58, 16, v60
	v_lshlrev_b32_e32 v59, 16, v61
	v_and_b32_e32 v61, 0xffff0000, v61
	v_and_b32_e32 v60, 0xffff0000, v60
	s_and_b64 s[62:63], s[62:63], s[42:43]
	s_and_saveexec_b64 s[42:43], s[62:63]
	s_cbranch_execz .LBB0_1111
	v_cmp_lt_i64_e32 vcc, s[50:51], v[54:55]
	v_pk_mul_f32 v[46:47], v[12:13], v[46:47]
	v_pk_mul_f32 v[66:67], v[14:15], v[52:53]
	v_cndmask_b32_e64 v62, 0, 1.0, vcc
	v_cmp_gt_i64_e32 vcc, s[56:57], v[54:55]
	v_pk_mul_f32 v[46:47], v[46:47], v[62:63] op_sel_hi:[1,0]
	v_pk_mul_f32 v[44:45], v[22:23], v[44:45]
	v_cndmask_b32_e64 v54, 0, 1.0, vcc
	v_pk_fma_f32 v[46:47], v[0:1], v[36:37], v[46:47]
	v_pk_mul_f32 v[44:45], v[44:45], v[62:63] op_sel_hi:[1,0]
	v_pk_fma_f32 v[46:47], v[66:67], v[54:55], v[46:47] op_sel_hi:[1,0,1]
	v_pk_mul_f32 v[50:51], v[4:5], v[50:51]
	v_pk_mul_f32 v[70:71], v[20:21], v[56:57]
	v_mul_f32_e32 v55, 0xbfb8aa3b, v46
	v_pk_fma_f32 v[44:45], v[8:9], v[38:39], v[44:45]
	v_pk_mul_f32 v[50:51], v[50:51], v[62:63] op_sel_hi:[1,0]
	v_pk_fma_f32 v[44:45], v[70:71], v[54:55], v[44:45] op_sel_hi:[1,0,1]
	v_pk_mul_f32 v[68:69], v[6:7], v[58:59]
	v_exp_f32_e32 v66, v55
	v_mul_f32_e32 v55, 0xbfb8aa3b, v44
	v_pk_fma_f32 v[50:51], v[24:25], v[40:41], v[50:51]
	v_exp_f32_e32 v70, v55
	v_pk_fma_f32 v[50:51], v[54:55], v[68:69], v[50:51] op_sel_hi:[0,1,1]
	v_mul_f32_e32 v55, 0xbfb8aa3b, v47
	v_exp_f32_e32 v67, v55
	v_pk_mul_f32 v[48:49], v[18:19], v[48:49]
	v_pk_mul_f32 v[72:73], v[2:3], v[60:61]
	v_pk_add_f32 v[66:67], v[66:67], 1.0 op_sel_hi:[1,0]
	s_nop 0
	s_nop 0
	s_nop 0
	v_div_scale_f32 v80, vcc, v66, v66, v46
	v_div_scale_f32 v81, vcc, v67, v67, v47
	v_rcp_f32_e32 v82, v80
	v_rcp_f32_e32 v83, v81
	v_div_scale_f32 v86, s[62:63], v46, v66, v46
	v_div_scale_f32 v87, vcc, v47, v67, v47
	v_pk_fma_f32 v[84:85], v[80:81], v[82:83], 1.0 op_sel_hi:[1,1,0] neg_lo:[1,0,0] neg_hi:[1,0,0]
	v_pk_fma_f32 v[82:83], v[84:85], v[82:83], v[82:83]
	v_pk_mul_f32 v[88:89], v[86:87], v[82:83]
	v_pk_fma_f32 v[84:85], v[80:81], v[88:89], v[86:87] neg_lo:[1,0,0] neg_hi:[1,0,0]
	v_pk_fma_f32 v[88:89], v[84:85], v[82:83], v[88:89]
	v_pk_fma_f32 v[84:85], v[80:81], v[88:89], v[86:87] neg_lo:[1,0,0] neg_hi:[1,0,0]
	v_div_fmas_f32 v85, v85, v83, v89
	s_mov_b64 vcc, s[62:63]
	s_nop 0
	v_div_fmas_f32 v84, v84, v82, v88
	v_div_fixup_f32 v47, v85, v67, v47
	v_div_fixup_f32 v46, v84, v66, v46
	v_pk_mul_f32 v[46:47], v[50:51], v[46:47]
	v_mul_f32_e32 v50, 0xbfb8aa3b, v45
	v_exp_f32_e32 v71, v50
	v_pk_mul_f32 v[48:49], v[48:49], v[62:63] op_sel_hi:[1,0]
	v_pk_add_f32 v[50:51], v[70:71], 1.0 op_sel_hi:[1,0]
	v_pk_fma_f32 v[48:49], v[16:17], v[42:43], v[48:49]
	s_nop 0
	v_pk_fma_f32 v[48:49], v[54:55], v[72:73], v[48:49] op_sel_hi:[0,1,1]
	s_nop 0
	s_nop 0
	v_div_scale_f32 v80, vcc, v50, v50, v44
	v_div_scale_f32 v81, vcc, v51, v51, v45
	v_rcp_f32_e32 v82, v80
	v_rcp_f32_e32 v83, v81
	v_div_scale_f32 v86, s[62:63], v44, v50, v44
	v_div_scale_f32 v87, vcc, v45, v51, v45
	v_pk_fma_f32 v[84:85], v[80:81], v[82:83], 1.0 op_sel_hi:[1,1,0] neg_lo:[1,0,0] neg_hi:[1,0,0]
	v_pk_fma_f32 v[82:83], v[84:85], v[82:83], v[82:83]
	v_pk_mul_f32 v[88:89], v[86:87], v[82:83]
	v_pk_fma_f32 v[84:85], v[80:81], v[88:89], v[86:87] neg_lo:[1,0,0] neg_hi:[1,0,0]
	v_pk_fma_f32 v[88:89], v[84:85], v[82:83], v[88:89]
	v_pk_fma_f32 v[84:85], v[80:81], v[88:89], v[86:87] neg_lo:[1,0,0] neg_hi:[1,0,0]
	v_div_fmas_f32 v85, v85, v83, v89
	s_mov_b64 vcc, s[62:63]
	s_nop 0
	v_div_fmas_f32 v84, v84, v82, v88
	v_div_fixup_f32 v45, v85, v51, v45
	v_div_fixup_f32 v44, v84, v50, v44
	v_pk_mul_f32 v[44:45], v[48:49], v[44:45]
	v_cvt_pk_bf16_f32 v45, v47, v45
	v_cvt_pk_bf16_f32 v44, v46, v44
	global_store_dwordx2 v[30:31], v[44:45], off
	s_branch .LBB0_1111
